# MLA prompt loop: running max folded into QK MFMA accumulator init (C=-m block), lazy rescale threshold 2^8, sub+exp merged
# speedup vs baseline: 1.0376x; 1.0117x over previous
.Lst_first:
	v_sub_f32_e32 v236, 0, v153
	v_sub_f32_e32 v237, 0, v153
	v_sub_f32_e32 v238, 0, v153
	v_sub_f32_e32 v239, 0, v153
	v_sub_f32_e32 v240, 0, v153
	v_sub_f32_e32 v241, 0, v153
	v_sub_f32_e32 v242, 0, v153
	v_sub_f32_e32 v243, 0, v153
	v_sub_f32_e32 v244, 0, v153
	v_sub_f32_e32 v245, 0, v153
	v_sub_f32_e32 v246, 0, v153
	v_sub_f32_e32 v247, 0, v153
	v_sub_f32_e32 v248, 0, v153
	v_sub_f32_e32 v249, 0, v153
	v_sub_f32_e32 v250, 0, v153
	v_sub_f32_e32 v251, 0, v153
	v_mov_b32_e32 v154, v153
	s_branch .Lst_subs_0
.Lst_entry:
	v_add_u32_e32 v216, s68, v143
	v_add_u32_e32 v216, 0x100, v216
	v_ashrrev_i32_e32 v217, 31, v216
	v_lshlrev_b64 v[218:219], 12, v[216:217]
	v_lshlrev_b64 v[216:217], 6, v[216:217]
	v_lshl_add_u64 v[216:217], v[126:127], 0, v[216:217]
	v_lshl_add_u64 v[218:219], v[128:129], 0, v[218:219]
	v_lshl_add_u64 v[216:217], v[216:217], 0, s[64:65]
	v_cndmask_b32_e64 v216, v216, v218, s[14:15]
	v_subrev_u32_e32 v190, s30, v216
	v_mov_b32_e32 v216, 0x1000
	v_mov_b32_e32 v217, 0x40000
	v_cndmask_b32_e64 v197, v216, v217, s[14:15]
	v_add_u32_e32 v216, s68, v146
	v_add_u32_e32 v216, 0x100, v216
	v_ashrrev_i32_e32 v217, 31, v216
	v_lshlrev_b64 v[218:219], 12, v[216:217]
	v_lshlrev_b64 v[216:217], 6, v[216:217]
	v_lshl_add_u64 v[216:217], v[130:131], 0, v[216:217]
	v_lshl_add_u64 v[218:219], v[132:133], 0, v[218:219]
	v_lshl_add_u64 v[216:217], v[216:217], 0, s[64:65]
	v_cndmask_b32_e64 v216, v216, v218, s[16:17]
	v_subrev_u32_e32 v191, s30, v216
	v_mov_b32_e32 v216, 0x1000
	v_mov_b32_e32 v217, 0x40000
	v_cndmask_b32_e64 v208, v216, v217, s[16:17]
	v_add_u32_e32 v216, s68, v139
	v_add_u32_e32 v216, 0x100, v216
	v_ashrrev_i32_e32 v217, 31, v216
	v_lshlrev_b64 v[218:219], 12, v[216:217]
	v_lshlrev_b64 v[216:217], 6, v[216:217]
	v_lshl_add_u64 v[216:217], v[134:135], 0, v[216:217]
	v_lshl_add_u64 v[218:219], v[136:137], 0, v[218:219]
	v_lshl_add_u64 v[216:217], v[216:217], 0, s[64:65]
	v_cndmask_b32_e64 v216, v216, v218, s[18:19]
	v_subrev_u32_e32 v196, s30, v216
	v_mov_b32_e32 v216, 0x1000
	v_mov_b32_e32 v217, 0x40000
	v_cndmask_b32_e64 v209, v216, v217, s[18:19]
	v_mov_b32_e32 v236, 0
	v_mov_b32_e32 v237, 0
	v_mov_b32_e32 v238, 0
	v_mov_b32_e32 v239, 0
	v_mov_b32_e32 v240, 0
	v_mov_b32_e32 v241, 0
	v_mov_b32_e32 v242, 0
	v_mov_b32_e32 v243, 0
	v_mov_b32_e32 v244, 0
	v_mov_b32_e32 v245, 0
	v_mov_b32_e32 v246, 0
	v_mov_b32_e32 v247, 0
	v_mov_b32_e32 v248, 0
	v_mov_b32_e32 v249, 0
	v_mov_b32_e32 v250, 0
	v_mov_b32_e32 v251, 0
.Lst_top:
	s_add_i32 s93, s69, 0
	s_and_b32 s92, s93, 1
	s_cmp_gt_i32 s93, s50
	s_cbranch_scc1 .Lst_noqk0
	s_mul_i32 s4, s92, 0x5400
	s_add_i32 s24, s4, 0
	v_add3_u32 v153, s24, v192, v142
	ds_read_b128 v[220:223], v153
	ds_read_b128 v[224:227], v153 offset:32
	ds_read_b128 v[228:231], v153 offset:64
	ds_read_b128 v[232:235], v153 offset:96
	ds_read_b128 v[126:129], v153 offset:256
	ds_read_b128 v[130:133], v153 offset:288
	ds_read_b128 v[134:137], v153 offset:10752
	ds_read_b128 v[212:215], v153 offset:10784
	ds_read_b128 v[154:157], v153 offset:10816
	ds_read_b128 v[158:161], v153 offset:10848
	ds_read_b128 v[204:207], v153 offset:11008
	ds_read_b128 v[186:189], v153 offset:11040
	s_waitcnt lgkmcnt(11)
	v_mfma_f32_32x32x16_bf16 v[48:63], v[220:223], v[64:67], v[236:251]
	s_waitcnt lgkmcnt(10)
	v_mfma_f32_32x32x16_bf16 v[48:63], v[224:227], v[68:71], v[48:63]
	s_waitcnt lgkmcnt(9)
	v_mfma_f32_32x32x16_bf16 v[48:63], v[228:231], v[72:75], v[48:63]
	s_waitcnt lgkmcnt(8)
	v_mfma_f32_32x32x16_bf16 v[48:63], v[232:235], v[76:79], v[48:63]
	s_waitcnt lgkmcnt(7)
	v_mfma_f32_32x32x16_bf16 v[48:63], v[126:129], v[80:83], v[48:63]
	s_waitcnt lgkmcnt(6)
	v_mfma_f32_32x32x16_bf16 v[48:63], v[130:133], v[84:87], v[48:63]
	s_waitcnt lgkmcnt(5)
	v_mfma_f32_32x32x16_bf16 v[32:47], v[134:137], v[64:67], v[236:251]
	s_waitcnt lgkmcnt(4)
	v_mfma_f32_32x32x16_bf16 v[32:47], v[212:215], v[68:71], v[32:47]
	s_waitcnt lgkmcnt(3)
	v_mfma_f32_32x32x16_bf16 v[32:47], v[154:157], v[72:75], v[32:47]
	s_waitcnt lgkmcnt(2)
	v_mfma_f32_32x32x16_bf16 v[32:47], v[158:161], v[76:79], v[32:47]
	s_waitcnt lgkmcnt(1)
	v_mfma_f32_32x32x16_bf16 v[32:47], v[204:207], v[80:83], v[32:47]
	s_waitcnt lgkmcnt(0)
	v_mfma_f32_32x32x16_bf16 v[32:47], v[186:189], v[84:87], v[32:47]
	v_max_f32_e32 v162, v48, v48
	v_max_f32_e32 v153, v49, v49
	v_max_f32_e32 v153, v162, v153
	v_max3_f32 v153, v153, v50, v51
	v_max3_f32 v153, v153, v52, v53
	v_max3_f32 v153, v153, v54, v55
	v_max3_f32 v153, v153, v56, v57
	v_max3_f32 v153, v153, v58, v59
	v_max3_f32 v153, v153, v60, v61
	v_max3_f32 v153, v153, v62, v63
	s_nop 1
	v_max3_f32 v153, v153, v32, v33
	v_max3_f32 v153, v153, v34, v35
	v_max3_f32 v153, v153, v36, v37
	v_max3_f32 v153, v153, v38, v39
	v_max3_f32 v153, v153, v40, v41
	v_max3_f32 v153, v153, v42, v43
	v_max3_f32 v153, v153, v44, v45
	v_max3_f32 v153, v153, v46, v47
	v_mov_b32_e32 v154, v153
	s_nop 1
	v_permlane32_swap_b32_e32 v153, v154
	v_max_f32_e32 v153, v153, v154
.Lst_noqk0:
	s_cmp_gt_i32 s93, s50
	s_cbranch_scc1 .Lst_nosm0
	s_cmp_eq_u32 s93, 0
	s_cbranch_scc1 .Lst_first
	v_cmp_lt_f32_e32 vcc, 0x41000000, v153
	s_cbranch_vccz .Lst_norescale_0
	v_max_f32_e32 v154, 0, v153
	v_exp_f32_e64 v152, -v154
	v_sub_f32_e32 v236, v236, v154
	v_sub_f32_e32 v237, v237, v154
	v_sub_f32_e32 v238, v238, v154
	v_sub_f32_e32 v239, v239, v154
	v_sub_f32_e32 v240, v240, v154
	v_sub_f32_e32 v241, v241, v154
	v_sub_f32_e32 v242, v242, v154
	v_sub_f32_e32 v243, v243, v154
	v_sub_f32_e32 v244, v244, v154
	v_sub_f32_e32 v245, v245, v154
	v_sub_f32_e32 v246, v246, v154
	v_sub_f32_e32 v247, v247, v154
	v_sub_f32_e32 v248, v248, v154
	v_sub_f32_e32 v249, v249, v154
	v_sub_f32_e32 v250, v250, v154
	v_sub_f32_e32 v251, v251, v154
	v_pk_mul_f32 v[30:31], v[30:31], v[152:153] op_sel_hi:[1,0]
	v_pk_mul_f32 v[28:29], v[28:29], v[152:153] op_sel_hi:[1,0]
	v_pk_mul_f32 v[26:27], v[26:27], v[152:153] op_sel_hi:[1,0]
	v_pk_mul_f32 v[24:25], v[24:25], v[152:153] op_sel_hi:[1,0]
	v_pk_mul_f32 v[22:23], v[22:23], v[152:153] op_sel_hi:[1,0]
	v_pk_mul_f32 v[20:21], v[20:21], v[152:153] op_sel_hi:[1,0]
	v_pk_mul_f32 v[18:19], v[18:19], v[152:153] op_sel_hi:[1,0]
	v_pk_mul_f32 v[16:17], v[16:17], v[152:153] op_sel_hi:[1,0]
	v_pk_mul_f32 v[14:15], v[14:15], v[152:153] op_sel_hi:[1,0]
	v_pk_mul_f32 v[12:13], v[12:13], v[152:153] op_sel_hi:[1,0]
	v_pk_mul_f32 v[10:11], v[10:11], v[152:153] op_sel_hi:[1,0]
	v_pk_mul_f32 v[8:9], v[8:9], v[152:153] op_sel_hi:[1,0]
	v_pk_mul_f32 v[6:7], v[6:7], v[152:153] op_sel_hi:[1,0]
	v_pk_mul_f32 v[4:5], v[4:5], v[152:153] op_sel_hi:[1,0]
	v_pk_mul_f32 v[2:3], v[2:3], v[152:153] op_sel_hi:[1,0]
	v_pk_mul_f32 v[0:1], v[0:1], v[152:153] op_sel_hi:[1,0]
	v_mul_f32_e32 v151, v151, v152
.Lst_subs_0:
	v_sub_f32_e32 v48, v48, v154
	v_sub_f32_e32 v49, v49, v154
	v_sub_f32_e32 v50, v50, v154
	v_sub_f32_e32 v51, v51, v154
	v_sub_f32_e32 v52, v52, v154
	v_sub_f32_e32 v53, v53, v154
	v_sub_f32_e32 v54, v54, v154
	v_sub_f32_e32 v55, v55, v154
	v_sub_f32_e32 v56, v56, v154
	v_sub_f32_e32 v57, v57, v154
	v_sub_f32_e32 v58, v58, v154
	v_sub_f32_e32 v59, v59, v154
	v_sub_f32_e32 v60, v60, v154
	v_sub_f32_e32 v61, v61, v154
	v_sub_f32_e32 v62, v62, v154
	v_sub_f32_e32 v63, v63, v154
	v_sub_f32_e32 v32, v32, v154
	v_sub_f32_e32 v33, v33, v154
	v_sub_f32_e32 v34, v34, v154
	v_sub_f32_e32 v35, v35, v154
	v_sub_f32_e32 v36, v36, v154
	v_sub_f32_e32 v37, v37, v154
	v_sub_f32_e32 v38, v38, v154
	v_sub_f32_e32 v39, v39, v154
	v_sub_f32_e32 v40, v40, v154
	v_sub_f32_e32 v41, v41, v154
	v_sub_f32_e32 v42, v42, v154
	v_sub_f32_e32 v43, v43, v154
	v_sub_f32_e32 v44, v44, v154
	v_sub_f32_e32 v45, v45, v154
	v_sub_f32_e32 v46, v46, v154
	v_sub_f32_e32 v47, v47, v154
.Lst_norescale_0:
	v_exp_f32_e32 v170, v32
	v_exp_f32_e32 v171, v33
	v_exp_f32_e32 v172, v34
	v_exp_f32_e32 v173, v35
	v_exp_f32_e32 v174, v36
	v_exp_f32_e32 v175, v37
	v_exp_f32_e32 v176, v38
	v_exp_f32_e32 v158, v52
	v_exp_f32_e32 v177, v39
	v_exp_f32_e32 v159, v53
	v_exp_f32_e32 v178, v40
	v_exp_f32_e32 v160, v54
	v_exp_f32_e32 v179, v41
	v_exp_f32_e32 v48, v48
	v_exp_f32_e32 v49, v49
	v_exp_f32_e32 v50, v50
	v_exp_f32_e32 v51, v51
	v_exp_f32_e32 v161, v55
	v_exp_f32_e32 v180, v42
	v_add3_u32 v155, s24, v140, v141
	v_exp_f32_e32 v162, v56
	v_exp_f32_e32 v181, v43
	ds_read_b64_tr_b16 v[36:37], v155 offset:128
	ds_read_b64_tr_b16 v[38:39], v155 offset:2816
	v_exp_f32_e32 v163, v57
	v_exp_f32_e32 v182, v44
	v_exp_f32_e32 v164, v58
	v_exp_f32_e32 v183, v45
	v_exp_f32_e32 v165, v59
	v_exp_f32_e32 v184, v46
	v_exp_f32_e32 v166, v60
	v_cvt_pk_bf16_f32 v32, v48, v49
	v_cvt_pk_bf16_f32 v33, v50, v51
	v_cvt_pk_bf16_f32 v34, v158, v159
	v_cvt_pk_bf16_f32 v35, v160, v161
	v_exp_f32_e32 v167, v61
	s_waitcnt lgkmcnt(0)
	v_mfma_f32_32x32x16_bf16 v[16:31], v[36:39], v[32:35], v[16:31]
	v_exp_f32_e32 v168, v62
	v_exp_f32_e32 v169, v63
	v_add_f32_e32 v153, v49, v48
	v_add_f32_e32 v153, v50, v153
	v_add_f32_e32 v153, v51, v153
	v_exp_f32_e32 v185, v47
	ds_read_b64_tr_b16 v[44:45], v155 offset:5504
	ds_read_b64_tr_b16 v[46:47], v155 offset:8192
	ds_read_b64_tr_b16 v[50:51], v155 offset:2880
	ds_read_b64_tr_b16 v[48:49], v155 offset:192
	v_cvt_pk_bf16_f32 v40, v162, v163
	v_cvt_pk_bf16_f32 v41, v164, v165
	v_cvt_pk_bf16_f32 v42, v166, v167
	v_cvt_pk_bf16_f32 v43, v168, v169
	ds_read_b64_tr_b16 v[52:53], v155 offset:10880
	ds_read_b64_tr_b16 v[54:55], v155 offset:13568
	ds_read_b64_tr_b16 v[58:59], v155 offset:8256
	ds_read_b64_tr_b16 v[56:57], v155 offset:5568
	s_waitcnt lgkmcnt(6)
	v_mfma_f32_32x32x16_bf16 v[16:31], v[44:47], v[40:43], v[16:31]
	v_cvt_pk_bf16_f32 v36, v170, v171
	v_cvt_pk_bf16_f32 v37, v172, v173
	v_cvt_pk_bf16_f32 v38, v174, v175
	v_cvt_pk_bf16_f32 v39, v176, v177
	ds_read_b64_tr_b16 v[44:45], v155 offset:16256
	ds_read_b64_tr_b16 v[46:47], v155 offset:18944
	ds_read_b64_tr_b16 v[62:63], v155 offset:13632
	ds_read_b64_tr_b16 v[60:61], v155 offset:10944
	ds_read_b64_tr_b16 v[156:157], v155 offset:19008
	ds_read_b64_tr_b16 v[154:155], v155 offset:16320
	s_waitcnt lgkmcnt(8)
	v_mfma_f32_32x32x16_bf16 v[16:31], v[52:55], v[36:39], v[16:31]
	v_cvt_pk_bf16_f32 v52, v178, v179
	v_cvt_pk_bf16_f32 v53, v180, v181
	v_cvt_pk_bf16_f32 v54, v182, v183
	v_cvt_pk_bf16_f32 v55, v184, v185
	v_mfma_f32_32x32x16_bf16 v[0:15], v[48:51], v[32:35], v[0:15]
	s_waitcnt lgkmcnt(4)
	v_mfma_f32_32x32x16_bf16 v[16:31], v[44:47], v[52:55], v[16:31]
	v_add_f32_e32 v44, v158, v153
	v_add_f32_e32 v44, v159, v44
	v_add_f32_e32 v44, v160, v44
	v_add_f32_e32 v44, v161, v44
	v_add_f32_e32 v44, v162, v44
	v_add_f32_e32 v44, v163, v44
	v_add_f32_e32 v44, v164, v44
	v_mfma_f32_32x32x16_bf16 v[0:15], v[56:59], v[40:43], v[0:15]
	v_add_f32_e32 v32, v165, v44
	v_add_f32_e32 v32, v166, v32
	v_add_f32_e32 v32, v167, v32
	v_add_f32_e32 v32, v168, v32
	v_add_f32_e32 v32, v169, v32
	v_add_f32_e32 v32, v170, v32
	v_add_f32_e32 v32, v171, v32
	s_waitcnt lgkmcnt(2)
	v_mfma_f32_32x32x16_bf16 v[0:15], v[60:63], v[36:39], v[0:15]
	v_add_f32_e32 v32, v172, v32
	v_add_f32_e32 v32, v173, v32
	v_add_f32_e32 v32, v174, v32
	v_add_f32_e32 v32, v175, v32
	v_add_f32_e32 v32, v176, v32
	v_add_f32_e32 v32, v177, v32
	v_add_f32_e32 v32, v178, v32
	v_add_f32_e32 v32, v179, v32
	s_waitcnt lgkmcnt(0)
	v_mfma_f32_32x32x16_bf16 v[0:15], v[154:157], v[52:55], v[0:15]
	v_add_f32_e32 v32, v180, v32
	v_add_f32_e32 v32, v181, v32
	v_add_f32_e32 v32, v182, v32
	v_add_f32_e32 v32, v183, v32
	v_add_f32_e32 v32, v184, v32
	v_add_f32_e32 v32, v185, v32
	v_add_f32_e32 v151, v151, v32

.Lst_a0_nold:
.Lst_bar2_0:
	s_waitcnt lgkmcnt(0)
	s_barrier
	s_add_i32 s93, s69, 1
	s_cmp_ge_u32 s93, s47
	s_cbranch_scc1 .Lst_exit
	s_and_b32 s92, s93, 1
	s_cmp_gt_i32 s93, s50
	s_cbranch_scc1 .Lst_noqk1
	s_mul_i32 s4, s92, 0x5400
	s_add_i32 s24, s4, 0
	v_add3_u32 v153, s24, v192, v142
	ds_read_b128 v[220:223], v153
	ds_read_b128 v[224:227], v153 offset:32
	ds_read_b128 v[228:231], v153 offset:64
	ds_read_b128 v[232:235], v153 offset:96
	ds_read_b128 v[126:129], v153 offset:256
	ds_read_b128 v[130:133], v153 offset:288
	ds_read_b128 v[134:137], v153 offset:10752
	ds_read_b128 v[212:215], v153 offset:10784
	ds_read_b128 v[154:157], v153 offset:10816
	ds_read_b128 v[158:161], v153 offset:10848
	ds_read_b128 v[204:207], v153 offset:11008
	ds_read_b128 v[186:189], v153 offset:11040
	s_waitcnt lgkmcnt(11)
	v_mfma_f32_32x32x16_bf16 v[48:63], v[220:223], v[64:67], v[236:251]
	s_waitcnt lgkmcnt(10)
	v_mfma_f32_32x32x16_bf16 v[48:63], v[224:227], v[68:71], v[48:63]
	s_waitcnt lgkmcnt(9)
	v_mfma_f32_32x32x16_bf16 v[48:63], v[228:231], v[72:75], v[48:63]
	s_waitcnt lgkmcnt(8)
	v_mfma_f32_32x32x16_bf16 v[48:63], v[232:235], v[76:79], v[48:63]
	s_waitcnt lgkmcnt(7)
	v_mfma_f32_32x32x16_bf16 v[48:63], v[126:129], v[80:83], v[48:63]
	s_waitcnt lgkmcnt(6)
	v_mfma_f32_32x32x16_bf16 v[48:63], v[130:133], v[84:87], v[48:63]
	s_waitcnt lgkmcnt(5)
	v_mfma_f32_32x32x16_bf16 v[32:47], v[134:137], v[64:67], v[236:251]
	s_waitcnt lgkmcnt(4)
	v_mfma_f32_32x32x16_bf16 v[32:47], v[212:215], v[68:71], v[32:47]
	s_waitcnt lgkmcnt(3)
	v_mfma_f32_32x32x16_bf16 v[32:47], v[154:157], v[72:75], v[32:47]
	s_waitcnt lgkmcnt(2)
	v_mfma_f32_32x32x16_bf16 v[32:47], v[158:161], v[76:79], v[32:47]
	s_waitcnt lgkmcnt(1)
	v_mfma_f32_32x32x16_bf16 v[32:47], v[204:207], v[80:83], v[32:47]
	s_waitcnt lgkmcnt(0)
	v_mfma_f32_32x32x16_bf16 v[32:47], v[186:189], v[84:87], v[32:47]
	v_max_f32_e32 v162, v48, v48
	v_max_f32_e32 v153, v49, v49
	v_max_f32_e32 v153, v162, v153
	v_max3_f32 v153, v153, v50, v51
	v_max3_f32 v153, v153, v52, v53
	v_max3_f32 v153, v153, v54, v55
	v_max3_f32 v153, v153, v56, v57
	v_max3_f32 v153, v153, v58, v59
	v_max3_f32 v153, v153, v60, v61
	v_max3_f32 v153, v153, v62, v63
	s_nop 1
	v_max3_f32 v153, v153, v32, v33
	v_max3_f32 v153, v153, v34, v35
	v_max3_f32 v153, v153, v36, v37
	v_max3_f32 v153, v153, v38, v39
	v_max3_f32 v153, v153, v40, v41
	v_max3_f32 v153, v153, v42, v43
	v_max3_f32 v153, v153, v44, v45
	v_max3_f32 v153, v153, v46, v47
	v_mov_b32_e32 v154, v153
	s_nop 1
	v_permlane32_swap_b32_e32 v153, v154
	v_max_f32_e32 v153, v153, v154
.Lst_noqk1:
	s_cmp_gt_i32 s93, s50
	s_cbranch_scc1 .Lst_nosm1
	v_cmp_lt_f32_e32 vcc, 0x41000000, v153
	s_cbranch_vccz .Lst_norescale_1
	v_max_f32_e32 v154, 0, v153
	v_exp_f32_e64 v152, -v154
	v_sub_f32_e32 v236, v236, v154
	v_sub_f32_e32 v237, v237, v154
	v_sub_f32_e32 v238, v238, v154
	v_sub_f32_e32 v239, v239, v154
	v_sub_f32_e32 v240, v240, v154
	v_sub_f32_e32 v241, v241, v154
	v_sub_f32_e32 v242, v242, v154
	v_sub_f32_e32 v243, v243, v154
	v_sub_f32_e32 v244, v244, v154
	v_sub_f32_e32 v245, v245, v154
	v_sub_f32_e32 v246, v246, v154
	v_sub_f32_e32 v247, v247, v154
	v_sub_f32_e32 v248, v248, v154
	v_sub_f32_e32 v249, v249, v154
	v_sub_f32_e32 v250, v250, v154
	v_sub_f32_e32 v251, v251, v154
	v_pk_mul_f32 v[30:31], v[30:31], v[152:153] op_sel_hi:[1,0]
	v_pk_mul_f32 v[28:29], v[28:29], v[152:153] op_sel_hi:[1,0]
	v_pk_mul_f32 v[26:27], v[26:27], v[152:153] op_sel_hi:[1,0]
	v_pk_mul_f32 v[24:25], v[24:25], v[152:153] op_sel_hi:[1,0]
	v_pk_mul_f32 v[22:23], v[22:23], v[152:153] op_sel_hi:[1,0]
	v_pk_mul_f32 v[20:21], v[20:21], v[152:153] op_sel_hi:[1,0]
	v_pk_mul_f32 v[18:19], v[18:19], v[152:153] op_sel_hi:[1,0]
	v_pk_mul_f32 v[16:17], v[16:17], v[152:153] op_sel_hi:[1,0]
	v_pk_mul_f32 v[14:15], v[14:15], v[152:153] op_sel_hi:[1,0]
	v_pk_mul_f32 v[12:13], v[12:13], v[152:153] op_sel_hi:[1,0]
	v_pk_mul_f32 v[10:11], v[10:11], v[152:153] op_sel_hi:[1,0]
	v_pk_mul_f32 v[8:9], v[8:9], v[152:153] op_sel_hi:[1,0]
	v_pk_mul_f32 v[6:7], v[6:7], v[152:153] op_sel_hi:[1,0]
	v_pk_mul_f32 v[4:5], v[4:5], v[152:153] op_sel_hi:[1,0]
	v_pk_mul_f32 v[2:3], v[2:3], v[152:153] op_sel_hi:[1,0]
	v_pk_mul_f32 v[0:1], v[0:1], v[152:153] op_sel_hi:[1,0]
	v_mul_f32_e32 v151, v151, v152

.Lst_a1_nold:
.Lst_bar2_1:
	s_waitcnt lgkmcnt(0)
	s_barrier
	s_add_i32 s93, s69, 2
	s_cmp_ge_u32 s93, s47
	s_cbranch_scc1 .Lst_exit
	s_and_b32 s92, s93, 1
	s_cmp_gt_i32 s93, s50
	s_cbranch_scc1 .Lst_noqk2
	s_mul_i32 s4, s92, 0x5400
	s_add_i32 s24, s4, 0
	v_add3_u32 v153, s24, v192, v142
	ds_read_b128 v[220:223], v153
	ds_read_b128 v[224:227], v153 offset:32
	ds_read_b128 v[228:231], v153 offset:64
	ds_read_b128 v[232:235], v153 offset:96
	ds_read_b128 v[126:129], v153 offset:256
	ds_read_b128 v[130:133], v153 offset:288
	ds_read_b128 v[134:137], v153 offset:10752
	ds_read_b128 v[212:215], v153 offset:10784
	ds_read_b128 v[154:157], v153 offset:10816
	ds_read_b128 v[158:161], v153 offset:10848
	ds_read_b128 v[204:207], v153 offset:11008
	ds_read_b128 v[186:189], v153 offset:11040
	s_waitcnt lgkmcnt(11)
	v_mfma_f32_32x32x16_bf16 v[48:63], v[220:223], v[64:67], v[236:251]
	s_waitcnt lgkmcnt(10)
	v_mfma_f32_32x32x16_bf16 v[48:63], v[224:227], v[68:71], v[48:63]
	s_waitcnt lgkmcnt(9)
	v_mfma_f32_32x32x16_bf16 v[48:63], v[228:231], v[72:75], v[48:63]
	s_waitcnt lgkmcnt(8)
	v_mfma_f32_32x32x16_bf16 v[48:63], v[232:235], v[76:79], v[48:63]
	s_waitcnt lgkmcnt(7)
	v_mfma_f32_32x32x16_bf16 v[48:63], v[126:129], v[80:83], v[48:63]
	s_waitcnt lgkmcnt(6)
	v_mfma_f32_32x32x16_bf16 v[48:63], v[130:133], v[84:87], v[48:63]
	s_waitcnt lgkmcnt(5)
	v_mfma_f32_32x32x16_bf16 v[32:47], v[134:137], v[64:67], v[236:251]
	s_waitcnt lgkmcnt(4)
	v_mfma_f32_32x32x16_bf16 v[32:47], v[212:215], v[68:71], v[32:47]
	s_waitcnt lgkmcnt(3)
	v_mfma_f32_32x32x16_bf16 v[32:47], v[154:157], v[72:75], v[32:47]
	s_waitcnt lgkmcnt(2)
	v_mfma_f32_32x32x16_bf16 v[32:47], v[158:161], v[76:79], v[32:47]
	s_waitcnt lgkmcnt(1)
	v_mfma_f32_32x32x16_bf16 v[32:47], v[204:207], v[80:83], v[32:47]
	s_waitcnt lgkmcnt(0)
	v_mfma_f32_32x32x16_bf16 v[32:47], v[186:189], v[84:87], v[32:47]
	v_max_f32_e32 v162, v48, v48
	v_max_f32_e32 v153, v49, v49
	v_max_f32_e32 v153, v162, v153
	v_max3_f32 v153, v153, v50, v51
	v_max3_f32 v153, v153, v52, v53
	v_max3_f32 v153, v153, v54, v55
	v_max3_f32 v153, v153, v56, v57
	v_max3_f32 v153, v153, v58, v59
	v_max3_f32 v153, v153, v60, v61
	v_max3_f32 v153, v153, v62, v63
	s_nop 1
	v_max3_f32 v153, v153, v32, v33
	v_max3_f32 v153, v153, v34, v35
	v_max3_f32 v153, v153, v36, v37
	v_max3_f32 v153, v153, v38, v39
	v_max3_f32 v153, v153, v40, v41
	v_max3_f32 v153, v153, v42, v43
	v_max3_f32 v153, v153, v44, v45
	v_max3_f32 v153, v153, v46, v47
	v_mov_b32_e32 v154, v153
	s_nop 1
	v_permlane32_swap_b32_e32 v153, v154
	v_max_f32_e32 v153, v153, v154
